# v25 + phase-5 queue order: sample-stream units interleaved with prompt units (every 6th of the first 768 tickets)
# baseline (speedup 1.0000x reference)
; #define LAS __attribute__((address_space(3)))
; #define GASP __attribute__((address_space(1)))
; __device__ __forceinline__ void gate_unit(const Params& p, LAS unsigned char* L, int row0, int n, int g, int sample_b) {
;     unsigned char* ws = p.ws;
;     int tid = threadIdx.x; asm volatile("" : "+v"(tid));
;     const int lane = tid & 63, r = lane & 31, hi = lane >> 5, wid = __builtin_amdgcn_readfirstlane(tid >> 6);
;     const float* GVF = (const float*)(ws + O_GVF); const float* GST = (const float*)(ws + O_GST); const bf16_t* UB = (const bf16_t*)(ws + O_UB); const bf16_t* WSB = (const bf16_t*)(ws + O_WSB);
;     const float* lng = p.in[17]; const float* lnb = p.in[18]; const float* bs = p.in[20];
;     const int tb = wid & 3, dh = wid >> 2;
;     const bool active = tb * 32 < n;
;     const int nks = active ? min((tb + 1) * 2, n / 16) : 0;
;     const int t = tid >> 2, ch = tid & 3; const bool ldr = t < n;
;     f32x4 xv[8], sp[4];
;     if (ldr) { const float* src = GVF + (size_t)(row0 + t) * 512 + g * 128 + ch * 32; const GASP f32x4* sq = (const GASP f32x4*)(GST + (size_t)(row0 + t) * 16);
; #pragma unroll
;         for (int i = 0; i < 8; ++i) xv[i] = *(const GASP f32x4*)(src + 4 * i);
; #pragma unroll
;         for (int i = 0; i < 4; ++i) sp[i] = sq[i]; }
; __global__ void __launch_bounds__(512, 2) mega(Params p) {
;     ...
;             for (;;) {
;                 int u = queue_next(ctr, lds);
;                 if (u >= NU_S + NU_P + NU_G) break;
;                 const int parts = rep5 == REP5 ? 7 : REP5_PARTS;
;                 if (u < NU_S) { if (parts & 1) diff_unit<true>(p, lds, u >> 2, u & 3, 0, lam); continue; } u -= NU_S;
;                 if (u < NU_P) { const int qi = 15 - (u >> 6), bh = u & 63; if (rep5 == REP5) diff_unit<false>(p, lds, bh >> 2, bh & 3, qi, lam); else if (parts & 2) diff_unit<false, EXPER5>(p, lds, bh >> 2, bh & 3, qi, lam); continue; } u -= NU_P;
;                 if (parts & 4) { const int bc = u >> 2, g = u & 3; if (bc < 256) gate_unit(p, lds, bc * 128, 128, g, -1); else gate_unit(p, lds, NP + (bc - 256) * 32, 32, g, bc - 256); }
.LBB0_873:
	s_or_b64 exec, exec, s[6:7]
	s_waitcnt lgkmcnt(0)
	s_barrier
	ds_read_b32 v0, v173
	s_movk_i32 s5, 0x8ff
	s_mov_b64 s[6:7], -1
	s_waitcnt lgkmcnt(0)
	s_barrier
	v_cmp_lt_i32_e32 vcc, s5, v0
	v_readfirstlane_b32 s4, v0
	s_cbranch_vccnz .LBB0_870
	s_cmpk_gt_u32 s4, 0x2ff
	s_cbranch_scc1 .Lrm_done
	s_mul_hi_u32 s98, s4, 0xaaaaaaab
	s_lshr_b32 s98, s98, 2
	s_mul_i32 s99, s98, 6
	s_sub_u32 s99, s4, s99
	s_cmp_eq_u32 s99, 0
	s_cbranch_scc1 .Lrm_sample
	s_sub_u32 s4, s4, s98
	s_add_u32 s4, s4, 127
	s_branch .Lrm_done
.Lrm_sample:
	s_mov_b32 s4, s98
.Lrm_done:
	s_cmpk_gt_i32 s4, 0x7f
	s_cbranch_scc0 .LBB0_945
	s_cmpk_gt_u32 s4, 0x47f
	s_cbranch_scc0 .LBB0_922
	s_add_i32 s6, s4, 0xfffffb80
	s_lshr_b32 s14, s6, 2
	s_and_b32 s5, s4, 3
	s_cmpk_gt_u32 s6, 0x3ff
	s_mov_b64 s[6:7], -1
	s_cbranch_scc0 .LBB0_889
	v_mov_b32_e32 v61, v208
	s_nop 0
	v_ashrrev_i32_e32 v86, 2, v61
	v_readfirstlane_b32 s13, v61
	v_cmp_gt_i32_e64 s[8:9], 32, v86
	v_cmp_lt_i32_e32 vcc, 31, v86
	s_and_saveexec_b64 s[6:7], vcc
	s_xor_b64 s[6:7], exec, s[6:7]
	s_lshl_b32 s10, s5, 7
	s_or_saveexec_b64 s[6:7], s[6:7]
	s_lshl_b32 s15, s14, 5
	v_and_b32_e32 v87, 3, v61
	s_add_i32 s12, s15, 0x6000
	v_mov_b32_e32 v58, s10
	v_lshlrev_b32_e32 v74, 7, v87
	s_xor_b64 exec, exec, s[6:7]
	s_cbranch_execz .LBB0_881
	s_waitcnt vmcnt(7)
	v_add_u32_e32 v2, s12, v86
	v_ashrrev_i32_e32 v3, 31, v2
	v_lshlrev_b64 v[4:5], 11, v[2:3]
	v_lshl_add_u64 v[4:5], s[66:67], 0, v[4:5]
	s_lshl_b32 s30, s5, 9
	v_lshl_add_u64 v[4:5], v[4:5], 0, s[30:31]
	v_mov_b32_e32 v75, v1
	s_waitcnt vmcnt(0)
	v_lshl_add_u64 v[14:15], v[4:5], 0, v[74:75]
	v_lshlrev_b64 v[2:3], 6, v[2:3]
	v_lshl_add_u64 v[16:17], s[64:65], 0, v[2:3]
	global_load_dwordx4 v[22:25], v[14:15], off offset:48
	global_load_dwordx4 v[26:29], v[14:15], off offset:32
	global_load_dwordx4 v[30:33], v[14:15], off offset:16
	global_load_dwordx4 v[38:41], v[14:15], off
	global_load_dwordx4 v[2:5], v[14:15], off offset:112
	global_load_dwordx4 v[6:9], v[14:15], off offset:96
	global_load_dwordx4 v[10:13], v[14:15], off offset:80
	global_load_dwordx4 v[18:21], v[14:15], off offset:64
	global_load_dwordx4 v[42:45], v[16:17], off offset:48
	global_load_dwordx4 v[46:49], v[16:17], off offset:32
	global_load_dwordx4 v[50:53], v[16:17], off offset:16
	global_load_dwordx4 v[54:57], v[16:17], off
	s_lshl_b32 s10, s5, 7
	v_mov_b32_e32 v58, s10
